# v21 plus: grid barrier, the non-last workgroups of an XCD poll the cross-XCD release generation directly (same generation count) instead of the per-XCD copy republished by their XCD's last arriver; ac
# baseline (speedup 1.0000x reference)
; __device__ __forceinline__ unsigned xb_ld(unsigned* p)              { return __hip_atomic_load(p, __ATOMIC_RELAXED, __HIP_MEMORY_SCOPE_AGENT); }
; __device__ __forceinline__ unsigned xb_add(unsigned* p, unsigned v) { return __hip_atomic_fetch_add(p, v, __ATOMIC_RELAXED, __HIP_MEMORY_SCOPE_AGENT); }
; #define XB_SPIN(cond, bar) do { unsigned _sp = 0; while (cond) { __builtin_amdgcn_s_sleep(1); \
;     if ((++_sp & 255u) == 0u) { if (xb_ld(&(bar)[XB_TMO])) break; if (_sp > XB_SPIN_CAP) { atomicAdd(&(bar)[XB_TMO], 1u); break; } } } } while (0)
; __device__ __forceinline__ void xcd_barrier(const XcdBarrier& b) {
;     ...
;         const unsigned old = xb_add(&bar[XB_XSUB(b.x)], 1u);
;         const unsigned gen = old / nloc;
;         if (old + 1u == (gen + 1u) * nloc) {
;             __builtin_amdgcn_fence(__ATOMIC_RELEASE, "agent");
;             asm volatile("s_waitcnt vmcnt(0)" ::: "memory");
;             const unsigned og = xb_add(&bar[XB_TOP], 1u);
;             const unsigned tg = og / nx;
;             if (og + 1u == (tg + 1u) * nx) xb_add(&bar[XB_TOPGEN], 1u);
;             else XB_SPIN(xb_ld(&bar[XB_TOPGEN]) == tg, bar);
;             __builtin_amdgcn_fence(__ATOMIC_ACQUIRE, "agent");
;             xb_add(&bar[XB_XGEN(b.x)], 1u);
;             asm volatile("s_waitcnt vmcnt(0)" ::: "memory");
;         } else {
;             XB_SPIN(xb_ld(&bar[XB_XGEN(b.x)]) == gen, bar);
.LBB0_117:
	s_or_b64 exec, exec, s[14:15]
	v_cvt_f32_u32_e32 v4, v2
	s_waitcnt vmcnt(0)
	v_readfirstlane_b32 s12, v3
	v_sub_u32_e32 v3, 0, v2
	v_rcp_iflag_f32_e32 v4, v4
	v_add_u32_e32 v5, s12, v1
	v_mul_f32_e32 v4, 0x4f7ffffe, v4
	v_cvt_u32_f32_e32 v4, v4
	v_mul_lo_u32 v1, v3, v4
	v_mul_hi_u32 v1, v4, v1
	v_add_u32_e32 v1, v4, v1
	v_mul_hi_u32 v1, v5, v1
	v_mul_lo_u32 v3, v1, v2
	v_sub_u32_e32 v3, v5, v3
	v_add_u32_e32 v4, 1, v1
	v_cmp_ge_u32_e32 vcc, v3, v2
	s_nop 1
	v_cndmask_b32_e32 v1, v1, v4, vcc
	v_sub_u32_e32 v4, v3, v2
	v_cndmask_b32_e32 v3, v3, v4, vcc
	v_add_u32_e32 v4, 1, v1
	v_cmp_ge_u32_e32 vcc, v3, v2
	v_add_u32_e32 v3, 1, v5
	s_nop 0
	v_cndmask_b32_e32 v1, v1, v4, vcc
	v_mul_lo_u32 v4, v2, v1
	v_add_u32_e32 v2, v4, v2
	v_cmp_ne_u32_e32 vcc, v3, v2
	s_and_saveexec_b64 s[12:13], vcc
	s_xor_b64 s[12:13], exec, s[12:13]
	s_cbranch_execz .LBB0_131
	s_waitcnt lgkmcnt(0)
	v_mov_b32_e32 v0, 0x7500
	global_load_dword v0, v0, s[24:25] sc1
	s_add_u32 s18, s24, 0x7500
	s_addc_u32 s19, s25, 0
	s_waitcnt vmcnt(0)
	v_cmp_eq_u32_e32 vcc, v0, v1
	s_and_saveexec_b64 s[14:15], vcc
	s_cbranch_execz .LBB0_130
	s_add_u32 s16, s24, 0x4200
	s_addc_u32 s17, s25, 0
	s_mov_b32 s33, 1
	s_mov_b64 s[20:21], 0
	v_mov_b32_e32 v0, 0
	s_branch .LBB0_121

; __device__ __forceinline__ unsigned xb_ld(unsigned* p)              { return __hip_atomic_load(p, __ATOMIC_RELAXED, __HIP_MEMORY_SCOPE_AGENT); }
; __device__ __forceinline__ unsigned xb_add(unsigned* p, unsigned v) { return __hip_atomic_fetch_add(p, v, __ATOMIC_RELAXED, __HIP_MEMORY_SCOPE_AGENT); }
; #define XB_SPIN(cond, bar) do { unsigned _sp = 0; while (cond) { __builtin_amdgcn_s_sleep(1); \
;     if ((++_sp & 255u) == 0u) { if (xb_ld(&(bar)[XB_TMO])) break; if (_sp > XB_SPIN_CAP) { atomicAdd(&(bar)[XB_TMO], 1u); break; } } } } while (0)
; __device__ __forceinline__ void xcd_barrier(const XcdBarrier& b) {
;     ...
;         const unsigned old = xb_add(&bar[XB_XSUB(b.x)], 1u);
;         const unsigned gen = old / nloc;
;         if (old + 1u == (gen + 1u) * nloc) {
;             __builtin_amdgcn_fence(__ATOMIC_RELEASE, "agent");
;             asm volatile("s_waitcnt vmcnt(0)" ::: "memory");
;             const unsigned og = xb_add(&bar[XB_TOP], 1u);
;             const unsigned tg = og / nx;
;             if (og + 1u == (tg + 1u) * nx) xb_add(&bar[XB_TOPGEN], 1u);
;             else XB_SPIN(xb_ld(&bar[XB_TOPGEN]) == tg, bar);
;             __builtin_amdgcn_fence(__ATOMIC_ACQUIRE, "agent");
;             xb_add(&bar[XB_XGEN(b.x)], 1u);
;             asm volatile("s_waitcnt vmcnt(0)" ::: "memory");
;         } else {
;             XB_SPIN(xb_ld(&bar[XB_XGEN(b.x)]) == gen, bar);
.LBB0_328:
	s_or_b64 exec, exec, s[12:13]
	v_cvt_f32_u32_e32 v4, v2
	s_waitcnt vmcnt(0)
	v_readfirstlane_b32 s10, v3
	v_sub_u32_e32 v3, 0, v2
	v_rcp_iflag_f32_e32 v4, v4
	v_add_u32_e32 v5, s10, v1
	v_mul_f32_e32 v4, 0x4f7ffffe, v4
	v_cvt_u32_f32_e32 v4, v4
	v_mul_lo_u32 v1, v3, v4
	v_mul_hi_u32 v1, v4, v1
	v_add_u32_e32 v1, v4, v1
	v_mul_hi_u32 v1, v5, v1
	v_mul_lo_u32 v3, v1, v2
	v_sub_u32_e32 v3, v5, v3
	v_add_u32_e32 v4, 1, v1
	v_cmp_ge_u32_e32 vcc, v3, v2
	s_nop 1
	v_cndmask_b32_e32 v1, v1, v4, vcc
	v_sub_u32_e32 v4, v3, v2
	v_cndmask_b32_e32 v3, v3, v4, vcc
	v_add_u32_e32 v4, 1, v1
	v_cmp_ge_u32_e32 vcc, v3, v2
	v_add_u32_e32 v3, 1, v5
	s_nop 0
	v_cndmask_b32_e32 v1, v1, v4, vcc
	v_mul_lo_u32 v4, v2, v1
	v_add_u32_e32 v2, v4, v2
	v_cmp_ne_u32_e32 vcc, v3, v2
	s_and_saveexec_b64 s[10:11], vcc
	s_xor_b64 s[10:11], exec, s[10:11]
	s_cbranch_execz .LBB0_342
	s_waitcnt lgkmcnt(0)
	v_mov_b32_e32 v0, 0x7500
	global_load_dword v0, v0, s[24:25] sc1
	s_add_u32 s16, s24, 0x7500
	s_addc_u32 s17, s25, 0
	s_waitcnt vmcnt(0)
	v_cmp_eq_u32_e32 vcc, v0, v1
	s_and_saveexec_b64 s[12:13], vcc
	s_cbranch_execz .LBB0_341
	s_add_u32 s14, s24, 0x4200
	s_addc_u32 s15, s25, 0
	s_mov_b32 s30, 1
	s_mov_b64 s[18:19], 0
	v_mov_b32_e32 v0, 0
	s_branch .LBB0_332

; __device__ __forceinline__ unsigned xb_ld(unsigned* p)              { return __hip_atomic_load(p, __ATOMIC_RELAXED, __HIP_MEMORY_SCOPE_AGENT); }
; __device__ __forceinline__ unsigned xb_add(unsigned* p, unsigned v) { return __hip_atomic_fetch_add(p, v, __ATOMIC_RELAXED, __HIP_MEMORY_SCOPE_AGENT); }
; #define XB_SPIN(cond, bar) do { unsigned _sp = 0; while (cond) { __builtin_amdgcn_s_sleep(1); \
;     if ((++_sp & 255u) == 0u) { if (xb_ld(&(bar)[XB_TMO])) break; if (_sp > XB_SPIN_CAP) { atomicAdd(&(bar)[XB_TMO], 1u); break; } } } } while (0)
; __device__ __forceinline__ void xcd_barrier(const XcdBarrier& b) {
;     ...
;         const unsigned old = xb_add(&bar[XB_XSUB(b.x)], 1u);
;         const unsigned gen = old / nloc;
;         if (old + 1u == (gen + 1u) * nloc) {
;             __builtin_amdgcn_fence(__ATOMIC_RELEASE, "agent");
;             asm volatile("s_waitcnt vmcnt(0)" ::: "memory");
;             const unsigned og = xb_add(&bar[XB_TOP], 1u);
;             const unsigned tg = og / nx;
;             if (og + 1u == (tg + 1u) * nx) xb_add(&bar[XB_TOPGEN], 1u);
;             else XB_SPIN(xb_ld(&bar[XB_TOPGEN]) == tg, bar);
;             __builtin_amdgcn_fence(__ATOMIC_ACQUIRE, "agent");
;             xb_add(&bar[XB_XGEN(b.x)], 1u);
;             asm volatile("s_waitcnt vmcnt(0)" ::: "memory");
;         } else {
;             XB_SPIN(xb_ld(&bar[XB_XGEN(b.x)]) == gen, bar);
.LBB0_419:
	s_or_b64 exec, exec, s[22:23]
	v_cvt_f32_u32_e32 v4, v2
	s_waitcnt vmcnt(0)
	v_readfirstlane_b32 s11, v3
	v_sub_u32_e32 v3, 0, v2
	v_rcp_iflag_f32_e32 v4, v4
	v_add_u32_e32 v5, s11, v1
	v_mul_f32_e32 v4, 0x4f7ffffe, v4
	v_cvt_u32_f32_e32 v4, v4
	v_mul_lo_u32 v1, v3, v4
	v_mul_hi_u32 v1, v4, v1
	v_add_u32_e32 v1, v4, v1
	v_mul_hi_u32 v1, v5, v1
	v_mul_lo_u32 v3, v1, v2
	v_sub_u32_e32 v3, v5, v3
	v_add_u32_e32 v4, 1, v1
	v_cmp_ge_u32_e32 vcc, v3, v2
	s_nop 1
	v_cndmask_b32_e32 v1, v1, v4, vcc
	v_sub_u32_e32 v4, v3, v2
	v_cndmask_b32_e32 v3, v3, v4, vcc
	v_add_u32_e32 v4, 1, v1
	v_cmp_ge_u32_e32 vcc, v3, v2
	v_add_u32_e32 v3, 1, v5
	s_nop 0
	v_cndmask_b32_e32 v1, v1, v4, vcc
	v_mul_lo_u32 v4, v2, v1
	v_add_u32_e32 v2, v4, v2
	v_cmp_ne_u32_e32 vcc, v3, v2
	s_and_saveexec_b64 s[12:13], vcc
	s_xor_b64 s[22:23], exec, s[12:13]
	s_cbranch_execz .LBB0_433
	v_readlane_b32 s12, v247, 15
	v_readlane_b32 s13, v247, 16
	s_waitcnt lgkmcnt(0)
	s_nop 3
	global_load_dword v0, v173, s[12:13] sc1
	s_waitcnt vmcnt(0)
	v_cmp_eq_u32_e32 vcc, v0, v1
	s_and_saveexec_b64 s[28:29], vcc
	s_cbranch_execz .LBB0_432
	s_mov_b32 s11, 1
	s_mov_b64 s[36:37], 0
	s_branch .LBB0_423

; __device__ __forceinline__ unsigned xb_ld(unsigned* p)              { return __hip_atomic_load(p, __ATOMIC_RELAXED, __HIP_MEMORY_SCOPE_AGENT); }
; #define XB_SPIN(cond, bar) do { unsigned _sp = 0; while (cond) { __builtin_amdgcn_s_sleep(1); \
;     if ((++_sp & 255u) == 0u) { if (xb_ld(&(bar)[XB_TMO])) break; if (_sp > XB_SPIN_CAP) { atomicAdd(&(bar)[XB_TMO], 1u); break; } } } } while (0)
; __device__ __forceinline__ void xcd_barrier(const XcdBarrier& b) {
;     ...
;             XB_SPIN(xb_ld(&bar[XB_XGEN(b.x)]) == gen, bar);
.LBB0_427:
	v_readlane_b32 s12, v247, 15
	v_readlane_b32 s13, v247, 16
	s_add_i32 s11, s11, 1
	s_mov_b64 s[44:45], -1
	s_nop 2
	global_load_dword v0, v173, s[12:13] sc1
	s_waitcnt vmcnt(0)
	v_cmp_ne_u32_e32 vcc, v0, v1
	s_orn2_b64 s[42:43], vcc, exec
	s_branch .LBB0_422

; __device__ __forceinline__ unsigned xb_ld(unsigned* p)              { return __hip_atomic_load(p, __ATOMIC_RELAXED, __HIP_MEMORY_SCOPE_AGENT); }
; __device__ __forceinline__ unsigned xb_add(unsigned* p, unsigned v) { return __hip_atomic_fetch_add(p, v, __ATOMIC_RELAXED, __HIP_MEMORY_SCOPE_AGENT); }
; #define XB_SPIN(cond, bar) do { unsigned _sp = 0; while (cond) { __builtin_amdgcn_s_sleep(1); \
;     if ((++_sp & 255u) == 0u) { if (xb_ld(&(bar)[XB_TMO])) break; if (_sp > XB_SPIN_CAP) { atomicAdd(&(bar)[XB_TMO], 1u); break; } } } } while (0)
; __device__ __forceinline__ void xcd_barrier(const XcdBarrier& b) {
;     ...
;         const unsigned old = xb_add(&bar[XB_XSUB(b.x)], 1u);
;         const unsigned gen = old / nloc;
;         if (old + 1u == (gen + 1u) * nloc) {
;             __builtin_amdgcn_fence(__ATOMIC_RELEASE, "agent");
;             asm volatile("s_waitcnt vmcnt(0)" ::: "memory");
;             const unsigned og = xb_add(&bar[XB_TOP], 1u);
;             const unsigned tg = og / nx;
;             if (og + 1u == (tg + 1u) * nx) xb_add(&bar[XB_TOPGEN], 1u);
;             else XB_SPIN(xb_ld(&bar[XB_TOPGEN]) == tg, bar);
;             __builtin_amdgcn_fence(__ATOMIC_ACQUIRE, "agent");
;             xb_add(&bar[XB_XGEN(b.x)], 1u);
;             asm volatile("s_waitcnt vmcnt(0)" ::: "memory");
;         } else {
;             XB_SPIN(xb_ld(&bar[XB_XGEN(b.x)]) == gen, bar);
.LBB0_1389:
	s_or_b64 exec, exec, s[22:23]
	v_cvt_f32_u32_e32 v4, v2
	s_waitcnt vmcnt(0)
	v_readfirstlane_b32 s6, v3
	v_sub_u32_e32 v3, 0, v2
	v_rcp_iflag_f32_e32 v4, v4
	v_add_u32_e32 v5, s6, v1
	v_mul_f32_e32 v4, 0x4f7ffffe, v4
	v_cvt_u32_f32_e32 v4, v4
	v_mul_lo_u32 v1, v3, v4
	v_mul_hi_u32 v1, v4, v1
	v_add_u32_e32 v1, v4, v1
	v_mul_hi_u32 v1, v5, v1
	v_mul_lo_u32 v3, v1, v2
	v_sub_u32_e32 v3, v5, v3
	v_add_u32_e32 v4, 1, v1
	v_cmp_ge_u32_e32 vcc, v3, v2
	s_nop 1
	v_cndmask_b32_e32 v1, v1, v4, vcc
	v_sub_u32_e32 v4, v3, v2
	v_cndmask_b32_e32 v3, v3, v4, vcc
	v_add_u32_e32 v4, 1, v1
	v_cmp_ge_u32_e32 vcc, v3, v2
	v_add_u32_e32 v3, 1, v5
	s_nop 0
	v_cndmask_b32_e32 v1, v1, v4, vcc
	v_mul_lo_u32 v4, v2, v1
	v_add_u32_e32 v2, v4, v2
	v_cmp_ne_u32_e32 vcc, v3, v2
	s_and_saveexec_b64 s[16:17], vcc
	s_xor_b64 s[22:23], exec, s[16:17]
	s_cbranch_execz .LBB0_1403
	v_readlane_b32 s16, v247, 15
	v_readlane_b32 s17, v247, 16
	s_waitcnt lgkmcnt(0)
	s_nop 3
	global_load_dword v0, v173, s[16:17] sc1
	s_waitcnt vmcnt(0)
	v_cmp_eq_u32_e32 vcc, v0, v1
	s_and_saveexec_b64 s[28:29], vcc
	s_cbranch_execz .LBB0_1402
	s_mov_b32 s6, 1
	s_mov_b64 s[36:37], 0
	s_branch .LBB0_1393

; __device__ __forceinline__ unsigned xb_ld(unsigned* p)              { return __hip_atomic_load(p, __ATOMIC_RELAXED, __HIP_MEMORY_SCOPE_AGENT); }
; #define XB_SPIN(cond, bar) do { unsigned _sp = 0; while (cond) { __builtin_amdgcn_s_sleep(1); \
;     if ((++_sp & 255u) == 0u) { if (xb_ld(&(bar)[XB_TMO])) break; if (_sp > XB_SPIN_CAP) { atomicAdd(&(bar)[XB_TMO], 1u); break; } } } } while (0)
; __device__ __forceinline__ void xcd_barrier(const XcdBarrier& b) {
;     ...
;             XB_SPIN(xb_ld(&bar[XB_XGEN(b.x)]) == gen, bar);
.LBB0_1397:
	v_readlane_b32 s16, v247, 15
	v_readlane_b32 s17, v247, 16
	s_add_i32 s6, s6, 1
	s_mov_b64 s[44:45], -1
	s_nop 2
	global_load_dword v0, v173, s[16:17] sc1
	s_waitcnt vmcnt(0)
	v_cmp_ne_u32_e32 vcc, v0, v1
	s_orn2_b64 s[42:43], vcc, exec
	s_branch .LBB0_1392

; __device__ __forceinline__ unsigned xb_ld(unsigned* p)              { return __hip_atomic_load(p, __ATOMIC_RELAXED, __HIP_MEMORY_SCOPE_AGENT); }
; __device__ __forceinline__ unsigned xb_add(unsigned* p, unsigned v) { return __hip_atomic_fetch_add(p, v, __ATOMIC_RELAXED, __HIP_MEMORY_SCOPE_AGENT); }
; #define XB_SPIN(cond, bar) do { unsigned _sp = 0; while (cond) { __builtin_amdgcn_s_sleep(1); \
;     if ((++_sp & 255u) == 0u) { if (xb_ld(&(bar)[XB_TMO])) break; if (_sp > XB_SPIN_CAP) { atomicAdd(&(bar)[XB_TMO], 1u); break; } } } } while (0)
; __device__ __forceinline__ void xcd_barrier(const XcdBarrier& b) {
;     ...
;         const unsigned old = xb_add(&bar[XB_XSUB(b.x)], 1u);
;         const unsigned gen = old / nloc;
;         if (old + 1u == (gen + 1u) * nloc) {
;             __builtin_amdgcn_fence(__ATOMIC_RELEASE, "agent");
;             asm volatile("s_waitcnt vmcnt(0)" ::: "memory");
;             const unsigned og = xb_add(&bar[XB_TOP], 1u);
;             const unsigned tg = og / nx;
;             if (og + 1u == (tg + 1u) * nx) xb_add(&bar[XB_TOPGEN], 1u);
;             else XB_SPIN(xb_ld(&bar[XB_TOPGEN]) == tg, bar);
;             __builtin_amdgcn_fence(__ATOMIC_ACQUIRE, "agent");
;             xb_add(&bar[XB_XGEN(b.x)], 1u);
;             asm volatile("s_waitcnt vmcnt(0)" ::: "memory");
;         } else {
;             XB_SPIN(xb_ld(&bar[XB_XGEN(b.x)]) == gen, bar);
.LBB0_1541:
	s_or_b64 exec, exec, s[22:23]
	v_cvt_f32_u32_e32 v4, v2
	s_waitcnt vmcnt(0)
	v_readfirstlane_b32 s11, v3
	v_sub_u32_e32 v3, 0, v2
	v_rcp_iflag_f32_e32 v4, v4
	v_add_u32_e32 v5, s11, v1
	v_mul_f32_e32 v4, 0x4f7ffffe, v4
	v_cvt_u32_f32_e32 v4, v4
	v_mul_lo_u32 v1, v3, v4
	v_mul_hi_u32 v1, v4, v1
	v_add_u32_e32 v1, v4, v1
	v_mul_hi_u32 v1, v5, v1
	v_mul_lo_u32 v3, v1, v2
	v_sub_u32_e32 v3, v5, v3
	v_add_u32_e32 v4, 1, v1
	v_cmp_ge_u32_e32 vcc, v3, v2
	s_nop 1
	v_cndmask_b32_e32 v1, v1, v4, vcc
	v_sub_u32_e32 v4, v3, v2
	v_cndmask_b32_e32 v3, v3, v4, vcc
	v_add_u32_e32 v4, 1, v1
	v_cmp_ge_u32_e32 vcc, v3, v2
	v_add_u32_e32 v3, 1, v5
	s_nop 0
	v_cndmask_b32_e32 v1, v1, v4, vcc
	v_mul_lo_u32 v4, v2, v1
	v_add_u32_e32 v2, v4, v2
	v_cmp_ne_u32_e32 vcc, v3, v2
	s_and_saveexec_b64 s[12:13], vcc
	s_xor_b64 s[22:23], exec, s[12:13]
	s_cbranch_execz .LBB0_1555
	v_readlane_b32 s12, v247, 15
	v_readlane_b32 s13, v247, 16
	s_waitcnt lgkmcnt(0)
	s_nop 3
	global_load_dword v0, v173, s[12:13] sc1
	s_waitcnt vmcnt(0)
	v_cmp_eq_u32_e32 vcc, v0, v1
	s_and_saveexec_b64 s[36:37], vcc
	s_cbranch_execz .LBB0_1554
	s_mov_b32 s11, 1
	s_mov_b64 s[40:41], 0
	s_branch .LBB0_1545

; __device__ __forceinline__ unsigned xb_ld(unsigned* p)              { return __hip_atomic_load(p, __ATOMIC_RELAXED, __HIP_MEMORY_SCOPE_AGENT); }
; #define XB_SPIN(cond, bar) do { unsigned _sp = 0; while (cond) { __builtin_amdgcn_s_sleep(1); \
;     if ((++_sp & 255u) == 0u) { if (xb_ld(&(bar)[XB_TMO])) break; if (_sp > XB_SPIN_CAP) { atomicAdd(&(bar)[XB_TMO], 1u); break; } } } } while (0)
; __device__ __forceinline__ void xcd_barrier(const XcdBarrier& b) {
;     ...
;             XB_SPIN(xb_ld(&bar[XB_XGEN(b.x)]) == gen, bar);
.LBB0_1549:
	v_readlane_b32 s12, v247, 15
	v_readlane_b32 s13, v247, 16
	s_add_i32 s11, s11, 1
	s_mov_b64 s[46:47], -1
	s_nop 2
	global_load_dword v0, v173, s[12:13] sc1
	s_waitcnt vmcnt(0)
	v_cmp_ne_u32_e32 vcc, v0, v1
	s_orn2_b64 s[44:45], vcc, exec
	s_branch .LBB0_1544

; __device__ __forceinline__ unsigned xb_ld(unsigned* p)              { return __hip_atomic_load(p, __ATOMIC_RELAXED, __HIP_MEMORY_SCOPE_AGENT); }
; __device__ __forceinline__ unsigned xb_add(unsigned* p, unsigned v) { return __hip_atomic_fetch_add(p, v, __ATOMIC_RELAXED, __HIP_MEMORY_SCOPE_AGENT); }
; #define XB_SPIN(cond, bar) do { unsigned _sp = 0; while (cond) { __builtin_amdgcn_s_sleep(1); \
;     if ((++_sp & 255u) == 0u) { if (xb_ld(&(bar)[XB_TMO])) break; if (_sp > XB_SPIN_CAP) { atomicAdd(&(bar)[XB_TMO], 1u); break; } } } } while (0)
; __device__ __forceinline__ void xcd_barrier(const XcdBarrier& b) {
;     ...
;         const unsigned old = xb_add(&bar[XB_XSUB(b.x)], 1u);
;         const unsigned gen = old / nloc;
;         if (old + 1u == (gen + 1u) * nloc) {
;             __builtin_amdgcn_fence(__ATOMIC_RELEASE, "agent");
;             asm volatile("s_waitcnt vmcnt(0)" ::: "memory");
;             const unsigned og = xb_add(&bar[XB_TOP], 1u);
;             const unsigned tg = og / nx;
;             if (og + 1u == (tg + 1u) * nx) xb_add(&bar[XB_TOPGEN], 1u);
;             else XB_SPIN(xb_ld(&bar[XB_TOPGEN]) == tg, bar);
;             __builtin_amdgcn_fence(__ATOMIC_ACQUIRE, "agent");
;             xb_add(&bar[XB_XGEN(b.x)], 1u);
;             asm volatile("s_waitcnt vmcnt(0)" ::: "memory");
;         } else {
;             XB_SPIN(xb_ld(&bar[XB_XGEN(b.x)]) == gen, bar);
.LBB0_2162:
	s_or_b64 exec, exec, s[22:23]
	v_cvt_f32_u32_e32 v4, v2
	s_waitcnt vmcnt(0)
	v_readfirstlane_b32 s6, v3
	v_sub_u32_e32 v3, 0, v2
	v_rcp_iflag_f32_e32 v4, v4
	v_add_u32_e32 v5, s6, v1
	v_mul_f32_e32 v4, 0x4f7ffffe, v4
	v_cvt_u32_f32_e32 v4, v4
	v_mul_lo_u32 v1, v3, v4
	v_mul_hi_u32 v1, v4, v1
	v_add_u32_e32 v1, v4, v1
	v_mul_hi_u32 v1, v5, v1
	v_mul_lo_u32 v3, v1, v2
	v_sub_u32_e32 v3, v5, v3
	v_add_u32_e32 v4, 1, v1
	v_cmp_ge_u32_e32 vcc, v3, v2
	s_nop 1
	v_cndmask_b32_e32 v1, v1, v4, vcc
	v_sub_u32_e32 v4, v3, v2
	v_cndmask_b32_e32 v3, v3, v4, vcc
	v_add_u32_e32 v4, 1, v1
	v_cmp_ge_u32_e32 vcc, v3, v2
	v_add_u32_e32 v3, 1, v5
	s_nop 0
	v_cndmask_b32_e32 v1, v1, v4, vcc
	v_mul_lo_u32 v4, v2, v1
	v_add_u32_e32 v2, v4, v2
	v_cmp_ne_u32_e32 vcc, v3, v2
	s_and_saveexec_b64 s[14:15], vcc
	s_xor_b64 s[22:23], exec, s[14:15]
	s_cbranch_execz .LBB0_2176
	v_readlane_b32 s14, v247, 15
	v_readlane_b32 s15, v247, 16
	s_waitcnt lgkmcnt(0)
	s_nop 3
	global_load_dword v0, v173, s[14:15] sc1
	s_waitcnt vmcnt(0)
	v_cmp_eq_u32_e32 vcc, v0, v1
	s_and_saveexec_b64 s[26:27], vcc
	s_cbranch_execz .LBB0_2175
	s_mov_b32 s6, 1
	s_mov_b64 s[28:29], 0
	s_branch .LBB0_2166

; __device__ __forceinline__ unsigned xb_ld(unsigned* p)              { return __hip_atomic_load(p, __ATOMIC_RELAXED, __HIP_MEMORY_SCOPE_AGENT); }
; __device__ __forceinline__ unsigned xb_add(unsigned* p, unsigned v) { return __hip_atomic_fetch_add(p, v, __ATOMIC_RELAXED, __HIP_MEMORY_SCOPE_AGENT); }
; #define XB_SPIN(cond, bar) do { unsigned _sp = 0; while (cond) { __builtin_amdgcn_s_sleep(1); \
;     if ((++_sp & 255u) == 0u) { if (xb_ld(&(bar)[XB_TMO])) break; if (_sp > XB_SPIN_CAP) { atomicAdd(&(bar)[XB_TMO], 1u); break; } } } } while (0)
; __device__ __forceinline__ void xcd_barrier(const XcdBarrier& b) {
;     ...
;             else XB_SPIN(xb_ld(&bar[XB_TOPGEN]) == tg, bar);
;             __builtin_amdgcn_fence(__ATOMIC_ACQUIRE, "agent");
;             xb_add(&bar[XB_XGEN(b.x)], 1u);
;             asm volatile("s_waitcnt vmcnt(0)" ::: "memory");
;         } else {
;             XB_SPIN(xb_ld(&bar[XB_XGEN(b.x)]) == gen, bar);
.LBB0_2170:
	v_readlane_b32 s14, v247, 15
	v_readlane_b32 s15, v247, 16
	s_add_i32 s6, s6, 1
	s_mov_b64 s[42:43], -1
	s_nop 2
	global_load_dword v0, v173, s[14:15] sc1
	s_waitcnt vmcnt(0)
	v_cmp_ne_u32_e32 vcc, v0, v1
	s_orn2_b64 s[40:41], vcc, exec
	s_branch .LBB0_2165

; __device__ __forceinline__ unsigned xb_ld(unsigned* p)              { return __hip_atomic_load(p, __ATOMIC_RELAXED, __HIP_MEMORY_SCOPE_AGENT); }
; __device__ __forceinline__ unsigned xb_add(unsigned* p, unsigned v) { return __hip_atomic_fetch_add(p, v, __ATOMIC_RELAXED, __HIP_MEMORY_SCOPE_AGENT); }
; #define XB_SPIN(cond, bar) do { unsigned _sp = 0; while (cond) { __builtin_amdgcn_s_sleep(1); \
;     if ((++_sp & 255u) == 0u) { if (xb_ld(&(bar)[XB_TMO])) break; if (_sp > XB_SPIN_CAP) { atomicAdd(&(bar)[XB_TMO], 1u); break; } } } } while (0)
; __device__ __forceinline__ void xcd_barrier(const XcdBarrier& b) {
;     ...
;         const unsigned old = xb_add(&bar[XB_XSUB(b.x)], 1u);
;         const unsigned gen = old / nloc;
;         if (old + 1u == (gen + 1u) * nloc) {
;             __builtin_amdgcn_fence(__ATOMIC_RELEASE, "agent");
;             asm volatile("s_waitcnt vmcnt(0)" ::: "memory");
;             const unsigned og = xb_add(&bar[XB_TOP], 1u);
;             const unsigned tg = og / nx;
;             if (og + 1u == (tg + 1u) * nx) xb_add(&bar[XB_TOPGEN], 1u);
;             else XB_SPIN(xb_ld(&bar[XB_TOPGEN]) == tg, bar);
;             __builtin_amdgcn_fence(__ATOMIC_ACQUIRE, "agent");
;             xb_add(&bar[XB_XGEN(b.x)], 1u);
;             asm volatile("s_waitcnt vmcnt(0)" ::: "memory");
;         } else {
;             XB_SPIN(xb_ld(&bar[XB_XGEN(b.x)]) == gen, bar);
.LBB0_2258:
	s_or_b64 exec, exec, s[22:23]
	v_cvt_f32_u32_e32 v4, v2
	s_waitcnt vmcnt(0)
	v_readfirstlane_b32 s11, v3
	v_sub_u32_e32 v3, 0, v2
	v_rcp_iflag_f32_e32 v4, v4
	v_add_u32_e32 v5, s11, v1
	v_mul_f32_e32 v4, 0x4f7ffffe, v4
	v_cvt_u32_f32_e32 v4, v4
	v_mul_lo_u32 v1, v3, v4
	v_mul_hi_u32 v1, v4, v1
	v_add_u32_e32 v1, v4, v1
	v_mul_hi_u32 v1, v5, v1
	v_mul_lo_u32 v3, v1, v2
	v_sub_u32_e32 v3, v5, v3
	v_add_u32_e32 v4, 1, v1
	v_cmp_ge_u32_e32 vcc, v3, v2
	s_nop 1
	v_cndmask_b32_e32 v1, v1, v4, vcc
	v_sub_u32_e32 v4, v3, v2
	v_cndmask_b32_e32 v3, v3, v4, vcc
	v_add_u32_e32 v4, 1, v1
	v_cmp_ge_u32_e32 vcc, v3, v2
	v_add_u32_e32 v3, 1, v5
	s_nop 0
	v_cndmask_b32_e32 v1, v1, v4, vcc
	v_mul_lo_u32 v4, v2, v1
	v_add_u32_e32 v2, v4, v2
	v_cmp_ne_u32_e32 vcc, v3, v2
	s_and_saveexec_b64 s[14:15], vcc
	s_xor_b64 s[22:23], exec, s[14:15]
	s_cbranch_execz .LBB0_2272
	v_readlane_b32 s14, v247, 15
	v_readlane_b32 s15, v247, 16
	s_waitcnt lgkmcnt(0)
	s_nop 3
	global_load_dword v0, v173, s[14:15] sc1
	s_waitcnt vmcnt(0)
	v_cmp_eq_u32_e32 vcc, v0, v1
	s_and_saveexec_b64 s[36:37], vcc
	s_cbranch_execz .LBB0_2271
	s_mov_b32 s11, 1
	s_mov_b64 s[40:41], 0
	s_branch .LBB0_2262

; __device__ __forceinline__ unsigned xb_ld(unsigned* p)              { return __hip_atomic_load(p, __ATOMIC_RELAXED, __HIP_MEMORY_SCOPE_AGENT); }
; __device__ __forceinline__ unsigned xb_add(unsigned* p, unsigned v) { return __hip_atomic_fetch_add(p, v, __ATOMIC_RELAXED, __HIP_MEMORY_SCOPE_AGENT); }
; #define XB_SPIN(cond, bar) do { unsigned _sp = 0; while (cond) { __builtin_amdgcn_s_sleep(1); \
;     if ((++_sp & 255u) == 0u) { if (xb_ld(&(bar)[XB_TMO])) break; if (_sp > XB_SPIN_CAP) { atomicAdd(&(bar)[XB_TMO], 1u); break; } } } } while (0)
; __device__ __forceinline__ void xcd_barrier(const XcdBarrier& b) {
;     ...
;             else XB_SPIN(xb_ld(&bar[XB_TOPGEN]) == tg, bar);
;             __builtin_amdgcn_fence(__ATOMIC_ACQUIRE, "agent");
;             xb_add(&bar[XB_XGEN(b.x)], 1u);
;             asm volatile("s_waitcnt vmcnt(0)" ::: "memory");
;         } else {
;             XB_SPIN(xb_ld(&bar[XB_XGEN(b.x)]) == gen, bar);
.LBB0_2266:
	v_readlane_b32 s14, v247, 15
	v_readlane_b32 s15, v247, 16
	s_add_i32 s11, s11, 1
	s_mov_b64 s[46:47], -1
	s_nop 2
	global_load_dword v0, v173, s[14:15] sc1
	s_waitcnt vmcnt(0)
	v_cmp_ne_u32_e32 vcc, v0, v1
	s_orn2_b64 s[44:45], vcc, exec
	s_branch .LBB0_2261

; __device__ __forceinline__ unsigned xb_ld(unsigned* p)              { return __hip_atomic_load(p, __ATOMIC_RELAXED, __HIP_MEMORY_SCOPE_AGENT); }
; __device__ __forceinline__ unsigned xb_add(unsigned* p, unsigned v) { return __hip_atomic_fetch_add(p, v, __ATOMIC_RELAXED, __HIP_MEMORY_SCOPE_AGENT); }
; #define XB_SPIN(cond, bar) do { unsigned _sp = 0; while (cond) { __builtin_amdgcn_s_sleep(1); \
;     if ((++_sp & 255u) == 0u) { if (xb_ld(&(bar)[XB_TMO])) break; if (_sp > XB_SPIN_CAP) { atomicAdd(&(bar)[XB_TMO], 1u); break; } } } } while (0)
; __device__ __forceinline__ void xcd_barrier(const XcdBarrier& b) {
;     ...
;         const unsigned old = xb_add(&bar[XB_XSUB(b.x)], 1u);
;         const unsigned gen = old / nloc;
;         if (old + 1u == (gen + 1u) * nloc) {
;             __builtin_amdgcn_fence(__ATOMIC_RELEASE, "agent");
;             asm volatile("s_waitcnt vmcnt(0)" ::: "memory");
;             const unsigned og = xb_add(&bar[XB_TOP], 1u);
;             const unsigned tg = og / nx;
;             if (og + 1u == (tg + 1u) * nx) xb_add(&bar[XB_TOPGEN], 1u);
;             else XB_SPIN(xb_ld(&bar[XB_TOPGEN]) == tg, bar);
;             __builtin_amdgcn_fence(__ATOMIC_ACQUIRE, "agent");
;             xb_add(&bar[XB_XGEN(b.x)], 1u);
;             asm volatile("s_waitcnt vmcnt(0)" ::: "memory");
;         } else {
;             XB_SPIN(xb_ld(&bar[XB_XGEN(b.x)]) == gen, bar);
.LBB0_2550:
	s_or_b64 exec, exec, s[22:23]
	v_cvt_f32_u32_e32 v4, v2
	s_waitcnt vmcnt(0)
	v_readfirstlane_b32 s6, v3
	v_sub_u32_e32 v3, 0, v2
	v_rcp_iflag_f32_e32 v4, v4
	v_add_u32_e32 v5, s6, v1
	v_mul_f32_e32 v4, 0x4f7ffffe, v4
	v_cvt_u32_f32_e32 v4, v4
	v_mul_lo_u32 v1, v3, v4
	v_mul_hi_u32 v1, v4, v1
	v_add_u32_e32 v1, v4, v1
	v_mul_hi_u32 v1, v5, v1
	v_mul_lo_u32 v3, v1, v2
	v_sub_u32_e32 v3, v5, v3
	v_add_u32_e32 v4, 1, v1
	v_cmp_ge_u32_e32 vcc, v3, v2
	s_nop 1
	v_cndmask_b32_e32 v1, v1, v4, vcc
	v_sub_u32_e32 v4, v3, v2
	v_cndmask_b32_e32 v3, v3, v4, vcc
	v_add_u32_e32 v4, 1, v1
	v_cmp_ge_u32_e32 vcc, v3, v2
	v_add_u32_e32 v3, 1, v5
	s_nop 0
	v_cndmask_b32_e32 v1, v1, v4, vcc
	v_mul_lo_u32 v4, v2, v1
	v_add_u32_e32 v2, v4, v2
	v_cmp_ne_u32_e32 vcc, v3, v2
	s_and_saveexec_b64 s[16:17], vcc
	s_xor_b64 s[22:23], exec, s[16:17]
	s_cbranch_execz .LBB0_2564
	v_readlane_b32 s16, v247, 15
	v_readlane_b32 s17, v247, 16
	s_waitcnt lgkmcnt(0)
	s_nop 3
	global_load_dword v0, v173, s[16:17] sc1
	s_waitcnt vmcnt(0)
	v_cmp_eq_u32_e32 vcc, v0, v1
	s_and_saveexec_b64 s[30:31], vcc
	s_cbranch_execz .LBB0_2563
	s_mov_b32 s6, 1
	s_mov_b64 s[36:37], 0
	s_branch .LBB0_2554

; __device__ __forceinline__ unsigned xb_ld(unsigned* p)              { return __hip_atomic_load(p, __ATOMIC_RELAXED, __HIP_MEMORY_SCOPE_AGENT); }
; __device__ __forceinline__ unsigned xb_add(unsigned* p, unsigned v) { return __hip_atomic_fetch_add(p, v, __ATOMIC_RELAXED, __HIP_MEMORY_SCOPE_AGENT); }
; #define XB_SPIN(cond, bar) do { unsigned _sp = 0; while (cond) { __builtin_amdgcn_s_sleep(1); \
;     if ((++_sp & 255u) == 0u) { if (xb_ld(&(bar)[XB_TMO])) break; if (_sp > XB_SPIN_CAP) { atomicAdd(&(bar)[XB_TMO], 1u); break; } } } } while (0)
; __device__ __forceinline__ void xcd_barrier(const XcdBarrier& b) {
;     ...
;         const unsigned old = xb_add(&bar[XB_XSUB(b.x)], 1u);
;         const unsigned gen = old / nloc;
;         if (old + 1u == (gen + 1u) * nloc) {
;             __builtin_amdgcn_fence(__ATOMIC_RELEASE, "agent");
;             asm volatile("s_waitcnt vmcnt(0)" ::: "memory");
;             const unsigned og = xb_add(&bar[XB_TOP], 1u);
;             const unsigned tg = og / nx;
;             if (og + 1u == (tg + 1u) * nx) xb_add(&bar[XB_TOPGEN], 1u);
;             else XB_SPIN(xb_ld(&bar[XB_TOPGEN]) == tg, bar);
;             __builtin_amdgcn_fence(__ATOMIC_ACQUIRE, "agent");
;             xb_add(&bar[XB_XGEN(b.x)], 1u);
;             asm volatile("s_waitcnt vmcnt(0)" ::: "memory");
;         } else {
;             XB_SPIN(xb_ld(&bar[XB_XGEN(b.x)]) == gen, bar);
.LBB0_2618:
	s_or_b64 exec, exec, s[2:3]
	v_cvt_f32_u32_e32 v4, v2
	s_waitcnt vmcnt(0)
	v_readfirstlane_b32 s2, v3
	v_sub_u32_e32 v3, 0, v2
	v_rcp_iflag_f32_e32 v4, v4
	v_add_u32_e32 v5, s2, v1
	v_mul_f32_e32 v4, 0x4f7ffffe, v4
	v_cvt_u32_f32_e32 v4, v4
	v_mul_lo_u32 v1, v3, v4
	v_mul_hi_u32 v1, v4, v1
	v_add_u32_e32 v1, v4, v1
	v_mul_hi_u32 v1, v5, v1
	v_mul_lo_u32 v3, v1, v2
	v_sub_u32_e32 v3, v5, v3
	v_add_u32_e32 v4, 1, v1
	v_cmp_ge_u32_e32 vcc, v3, v2
	s_nop 1
	v_cndmask_b32_e32 v1, v1, v4, vcc
	v_sub_u32_e32 v4, v3, v2
	v_cndmask_b32_e32 v3, v3, v4, vcc
	v_add_u32_e32 v4, 1, v1
	v_cmp_ge_u32_e32 vcc, v3, v2
	v_add_u32_e32 v3, 1, v5
	s_nop 0
	v_cndmask_b32_e32 v1, v1, v4, vcc
	v_mul_lo_u32 v4, v2, v1
	v_add_u32_e32 v2, v4, v2
	v_cmp_ne_u32_e32 vcc, v3, v2
	s_and_saveexec_b64 s[2:3], vcc
	s_xor_b64 s[2:3], exec, s[2:3]
	s_cbranch_execz .LBB0_2632
	v_readlane_b32 s4, v247, 15
	s_waitcnt lgkmcnt(0)
	v_mov_b32_e32 v0, 0
	v_readlane_b32 s5, v247, 16
	s_nop 4
	global_load_dword v2, v0, s[4:5] sc1
	s_waitcnt vmcnt(0)
	v_cmp_eq_u32_e32 vcc, v2, v1
	s_and_saveexec_b64 s[4:5], vcc
	s_cbranch_execz .LBB0_2631
	s_mov_b32 s16, 1
	s_mov_b64 s[6:7], 0
	s_branch .LBB0_2622

; __device__ __forceinline__ unsigned xb_ld(unsigned* p)              { return __hip_atomic_load(p, __ATOMIC_RELAXED, __HIP_MEMORY_SCOPE_AGENT); }
; __device__ __forceinline__ unsigned xb_add(unsigned* p, unsigned v) { return __hip_atomic_fetch_add(p, v, __ATOMIC_RELAXED, __HIP_MEMORY_SCOPE_AGENT); }
; #define XB_SPIN(cond, bar) do { unsigned _sp = 0; while (cond) { __builtin_amdgcn_s_sleep(1); \
;     if ((++_sp & 255u) == 0u) { if (xb_ld(&(bar)[XB_TMO])) break; if (_sp > XB_SPIN_CAP) { atomicAdd(&(bar)[XB_TMO], 1u); break; } } } } while (0)
; __device__ __forceinline__ void xcd_barrier(const XcdBarrier& b) {
;     ...
;             else XB_SPIN(xb_ld(&bar[XB_TOPGEN]) == tg, bar);
;             __builtin_amdgcn_fence(__ATOMIC_ACQUIRE, "agent");
;             xb_add(&bar[XB_XGEN(b.x)], 1u);
;             asm volatile("s_waitcnt vmcnt(0)" ::: "memory");
;         } else {
;             XB_SPIN(xb_ld(&bar[XB_XGEN(b.x)]) == gen, bar);
.LBB0_2626:
	v_readlane_b32 s10, v247, 15
	v_readlane_b32 s11, v247, 16
	s_add_i32 s16, s16, 1
	s_mov_b64 s[12:13], -1
	s_nop 2
	global_load_dword v2, v0, s[10:11] sc1
	s_waitcnt vmcnt(0)
	v_cmp_ne_u32_e32 vcc, v2, v1
	s_orn2_b64 s[10:11], vcc, exec
	s_branch .LBB0_2621
